# v55: v54 + P2 K-loop head moved from 52 to 16 mod 64 (7 s_nop before the loop label, 9 after P2 so later code keeps its placement); P2 x3 probe showed -18 us per pass
# baseline (speedup 1.0000x reference)
; template <class Epi, class Sched, bool ALIGN_EPI = false, bool SP2 = false>
; __device__ __forceinline__ void gemm_phase(PG8_LAS unsigned char* lds, const Gemm g, const Sched& S, const Epi& E) {
;     ...
;         const bool has_next = S.next(ui + 1, nxt);
;         const char* nA = has_next ? (const char*)g.A + (size_t)nxt.pm * tstep : cA; const char* nB = has_next ? (const char*)g.Bt + (size_t)nxt.pn * tstep : cB;
;         for (int t = 0; t < nt; t += 2) {
;             const bool last = (t == nt - 2);
;             const char* a1 = cA + (size_t)(t + 1) * kstep;
;             const char* a2 = last ? nA : cA + (size_t)(t + 2) * kstep; const char* b2 = last ? nB : cB + (size_t)(t + 2) * kstep;
;     ...
; #pragma unroll
;         for (int a = 0; a < 2; ++a)
; #pragma unroll
;             for (int b = 0; b < 2; ++b)
; #pragma unroll
;                 for (int m = 0; m < 4; ++m)
; #pragma unroll
;                     for (int n = 0; n < 2; ++n) acc[a][b][m][n] = (f32x4){0.f, 0.f, 0.f, 0.f};
;         cur = nxt; cA = nA; cB = nB; ++ui;
.LBB0_182:
	s_ashr_i32 s39, s38, 31
	s_lshl_b64 s[10:11], s[38:39], 21
	s_add_u32 s70, s74, s10
	v_readlane_b32 s1, v247, 29
	s_addc_u32 s71, s1, s11
	s_and_b64 s[10:11], s[66:67], exec
	s_cselect_b32 s1, s71, s7
	s_cselect_b32 s12, s70, s6
	s_ashr_i32 s85, s84, 31
	s_lshl_b64 s[10:11], s[84:85], 21
	s_add_u32 s72, s36, s10
	s_addc_u32 s73, s37, s11
	s_and_b64 s[10:11], s[66:67], exec
	s_cselect_b32 s13, s73, s9
	s_cselect_b32 s14, s72, s8
	s_add_u32 s6, s6, 0x100080
	s_addc_u32 s7, s7, 0
	s_add_u32 s15, s8, 0x100
	v_mov_b32_e32 v2, 0
	s_addc_u32 s16, s9, 0
	s_mov_b32 s17, -2
	v_mov_b32_e32 v3, v2
	v_mov_b32_e32 v4, v2
	v_mov_b32_e32 v5, v2
	v_mov_b32_e32 v6, v2
	v_mov_b32_e32 v7, v2
	v_mov_b32_e32 v8, v2
	v_mov_b32_e32 v9, v2
	v_mov_b32_e32 v14, v2
	v_mov_b32_e32 v15, v2
	v_mov_b32_e32 v16, v2
	v_mov_b32_e32 v17, v2
	v_mov_b32_e32 v22, v2
	v_mov_b32_e32 v23, v2
	v_mov_b32_e32 v24, v2
	v_mov_b32_e32 v25, v2
	v_mov_b32_e32 v30, v2
	v_mov_b32_e32 v31, v2
	v_mov_b32_e32 v32, v2
	v_mov_b32_e32 v33, v2
	v_mov_b32_e32 v38, v2
	v_mov_b32_e32 v39, v2
	v_mov_b32_e32 v40, v2
	v_mov_b32_e32 v41, v2
	v_mov_b32_e32 v46, v2
	v_mov_b32_e32 v47, v2
	v_mov_b32_e32 v48, v2
	v_mov_b32_e32 v49, v2
	v_mov_b32_e32 v54, v2
	v_mov_b32_e32 v55, v2
	v_mov_b32_e32 v56, v2
	v_mov_b32_e32 v57, v2
	v_mov_b32_e32 v10, v2
	v_mov_b32_e32 v11, v2
	v_mov_b32_e32 v12, v2
	v_mov_b32_e32 v13, v2
	v_mov_b32_e32 v18, v2
	v_mov_b32_e32 v19, v2
	v_mov_b32_e32 v20, v2
	v_mov_b32_e32 v21, v2
	v_mov_b32_e32 v26, v2
	v_mov_b32_e32 v27, v2
	v_mov_b32_e32 v28, v2
	v_mov_b32_e32 v29, v2
	v_mov_b32_e32 v34, v2
	v_mov_b32_e32 v35, v2
	v_mov_b32_e32 v36, v2
	v_mov_b32_e32 v37, v2
	v_mov_b32_e32 v42, v2
	v_mov_b32_e32 v43, v2
	v_mov_b32_e32 v44, v2
	v_mov_b32_e32 v45, v2
	v_mov_b32_e32 v50, v2
	v_mov_b32_e32 v51, v2
	v_mov_b32_e32 v52, v2
	v_mov_b32_e32 v53, v2
	v_mov_b32_e32 v58, v2
	v_mov_b32_e32 v59, v2
	v_mov_b32_e32 v60, v2
	v_mov_b32_e32 v61, v2
	v_mov_b32_e32 v62, v2
	v_mov_b32_e32 v63, v2
	v_mov_b32_e32 v64, v2
	v_mov_b32_e32 v65, v2
	v_mov_b32_e32 v66, v2
	v_mov_b32_e32 v67, v2
	v_mov_b32_e32 v68, v2
	v_mov_b32_e32 v69, v2
	v_mov_b32_e32 v70, v2
	v_mov_b32_e32 v71, v2
	v_mov_b32_e32 v72, v2
	v_mov_b32_e32 v73, v2
	v_mov_b32_e32 v78, v2
	v_mov_b32_e32 v79, v2
	v_mov_b32_e32 v80, v2
	v_mov_b32_e32 v81, v2
	v_mov_b32_e32 v86, v2
	v_mov_b32_e32 v87, v2
	v_mov_b32_e32 v88, v2
	v_mov_b32_e32 v89, v2
	v_mov_b32_e32 v94, v2
	v_mov_b32_e32 v95, v2
	v_mov_b32_e32 v96, v2
	v_mov_b32_e32 v97, v2
	v_mov_b32_e32 v102, v2
	v_mov_b32_e32 v103, v2
	v_mov_b32_e32 v104, v2
	v_mov_b32_e32 v105, v2
	v_mov_b32_e32 v110, v2
	v_mov_b32_e32 v111, v2
	v_mov_b32_e32 v112, v2
	v_mov_b32_e32 v113, v2
	v_mov_b32_e32 v118, v2
	v_mov_b32_e32 v119, v2
	v_mov_b32_e32 v120, v2
	v_mov_b32_e32 v121, v2
	v_mov_b32_e32 v74, v2
	v_mov_b32_e32 v75, v2
	v_mov_b32_e32 v76, v2
	v_mov_b32_e32 v77, v2
	v_mov_b32_e32 v82, v2
	v_mov_b32_e32 v83, v2
	v_mov_b32_e32 v84, v2
	v_mov_b32_e32 v85, v2
	v_mov_b32_e32 v90, v2
	v_mov_b32_e32 v91, v2
	v_mov_b32_e32 v92, v2
	v_mov_b32_e32 v93, v2
	v_mov_b32_e32 v98, v2
	v_mov_b32_e32 v99, v2
	v_mov_b32_e32 v100, v2
	v_mov_b32_e32 v101, v2
	v_mov_b32_e32 v106, v2
	v_mov_b32_e32 v107, v2
	v_mov_b32_e32 v108, v2
	v_mov_b32_e32 v109, v2
	v_mov_b32_e32 v114, v2
	v_mov_b32_e32 v115, v2
	v_mov_b32_e32 v116, v2
	v_mov_b32_e32 v117, v2
	v_mov_b32_e32 v122, v2
	v_mov_b32_e32 v123, v2
	v_mov_b32_e32 v124, v2
	v_mov_b32_e32 v125, v2
	v_mov_b32_e32 v126, v2
	v_mov_b32_e32 v127, v2
	v_mov_b32_e32 v128, v2
	v_mov_b32_e32 v129, v2
	s_waitcnt lgkmcnt(0)
	s_nop 0
	s_nop 0
	s_nop 0
	s_nop 0
	s_nop 0
	s_nop 0
	s_nop 0

; #define PG8_WAIT_V(n) asm volatile("s_waitcnt vmcnt(" #n ")" ::: "memory")
; #define PG8_BAR __builtin_amdgcn_s_barrier()
; template <class Epi, class Sched, bool ALIGN_EPI = false, bool SP2 = false>
; __device__ __forceinline__ void gemm_phase(PG8_LAS unsigned char* lds, const Gemm g, const Sched& S, const Epi& E) {
;     ...
;     PG8_WAIT_V(0);
;     if constexpr (!ALIGN_EPI) { if (wr == 0) PG8_BAR; }
;     PG8_BAR;
.LBB0_225:
	s_waitcnt vmcnt(0)
	v_readlane_b32 s56, v247, 40
	v_readlane_b32 s50, v247, 42
	v_readlane_b32 s70, v247, 44
	v_readlane_b32 s84, v247, 47
	v_readlane_b32 s57, v247, 41
	v_readlane_b32 s51, v247, 43
	v_readlane_b32 s71, v247, 45
	s_mov_b32 s75, s61
	v_readlane_b32 s85, v247, 48
	s_barrier
	s_nop 0
	s_nop 0
	s_nop 0
	s_nop 0
	s_nop 0
	s_nop 0
	s_nop 0
	s_nop 0
	s_nop 0
